# speedup vs baseline: 1.0043x; 1.0029x over previous
; __device__ __forceinline__ void phase0(const Params& P, char* lds) {
;     ...
;   const size_t n4 = (size_t)TOK * DM / 4;
;   for (size_t i = (size_t)bid * NTH + tid; i < n4; i += (size_t)G * NTH) {
;     f32x4 v = ((const f32x4*)P.x)[i];
;     u32x2 w = {cvtpk(v[0], v[1]), cvtpk(v[2], v[3])};
;     ((u32x2*)P_xb)[i] = w;
;   }
.LBB0_73:
	s_or_b64 exec, exec, s[6:7]
	s_ashr_i32 s89, s88, 31
	s_lshl_b64 s[0:1], s[88:89], 9
	v_ashrrev_i32_e32 v33, 31, v32
	v_lshl_add_u64 v[0:1], s[0:1], 0, v[32:33]
	s_mov_b64 s[0:1], 0x800000
	v_cmp_gt_u64_e32 vcc, s[0:1], v[0:1]
	s_and_saveexec_b64 s[4:5], vcc
	v_readlane_b32 s16, v250, 2
	s_mov_b64 s[72:73], s[76:77]
	s_mov_b64 s[76:77], s[80:81]
	v_readlane_b32 s17, v250, 3
	s_mov_b64 s[78:79], s[82:83]
	v_readlane_b32 s18, v250, 4
	v_readlane_b32 s19, v250, 5
	v_readlane_b32 s20, v250, 6
	v_readlane_b32 s21, v250, 7
	v_readlane_b32 s22, v250, 8
	v_readlane_b32 s23, v250, 9
	v_readlane_b32 s24, v250, 10
	v_readlane_b32 s25, v250, 11
	v_readlane_b32 s26, v250, 12
	v_readlane_b32 s27, v250, 13
	v_readlane_b32 s28, v250, 14
	v_readlane_b32 s29, v250, 15
	v_readlane_b32 s30, v250, 16
	v_readlane_b32 s31, v250, 17
	s_cbranch_execz .LBB0_76
	s_ashr_i32 s91, s90, 31
	s_mov_b64 s[8:9], s[16:17]
	s_lshl_b64 s[6:7], s[90:91], 9
	s_lshl_b64 s[0:1], s[88:89], 13
	s_add_u32 s0, s8, s0
	s_addc_u32 s1, s9, s1
	v_lshl_add_u64 v[2:3], v[32:33], 4, s[0:1]
	s_lshl_b64 s[8:9], s[90:91], 13
	s_lshl_b64 s[0:1], s[88:89], 12
	s_add_u32 s0, s94, s0
	s_addc_u32 s1, s95, s1
	v_lshl_add_u64 v[4:5], v[32:33], 3, s[0:1]
	s_mov_b64 s[0:1], 0x10e10000
	v_lshl_add_u64 v[4:5], v[4:5], 0, s[0:1]
	s_lshl_b64 s[0:1], s[90:91], 12
	s_mov_b64 s[2:3], 0
	s_mov_b64 s[12:13], 0x7fffff
	s_cmp_lg_u32 s90, 0x100
	s_cbranch_scc1 .LBB0_75
	global_load_dwordx4 v[60:63], v[2:3], off
	v_lshl_add_u64 v[2:3], v[2:3], 0, s[8:9]
	global_load_dwordx4 v[64:67], v[2:3], off
	v_lshl_add_u64 v[2:3], v[2:3], 0, s[8:9]
	global_load_dwordx4 v[68:71], v[2:3], off
	v_lshl_add_u64 v[2:3], v[2:3], 0, s[8:9]
	global_load_dwordx4 v[72:75], v[2:3], off
	v_lshl_add_u64 v[2:3], v[2:3], 0, s[8:9]
	global_load_dwordx4 v[112:115], v[2:3], off
	v_lshl_add_u64 v[2:3], v[2:3], 0, s[8:9]
	global_load_dwordx4 v[116:119], v[2:3], off
	v_lshl_add_u64 v[2:3], v[2:3], 0, s[8:9]
	global_load_dwordx4 v[120:123], v[2:3], off
	v_lshl_add_u64 v[2:3], v[2:3], 0, s[8:9]
	global_load_dwordx4 v[124:127], v[2:3], off
	v_lshl_add_u64 v[2:3], v[2:3], 0, s[8:9]
	global_load_dwordx4 v[128:131], v[2:3], off
	v_lshl_add_u64 v[2:3], v[2:3], 0, s[8:9]
	global_load_dwordx4 v[132:135], v[2:3], off
	v_lshl_add_u64 v[2:3], v[2:3], 0, s[8:9]
	global_load_dwordx4 v[136:139], v[2:3], off
	v_lshl_add_u64 v[2:3], v[2:3], 0, s[8:9]
	global_load_dwordx4 v[140:143], v[2:3], off
	v_lshl_add_u64 v[2:3], v[2:3], 0, s[8:9]
	global_load_dwordx4 v[144:147], v[2:3], off
	v_lshl_add_u64 v[2:3], v[2:3], 0, s[8:9]
	global_load_dwordx4 v[148:151], v[2:3], off
	v_lshl_add_u64 v[2:3], v[2:3], 0, s[8:9]
	global_load_dwordx4 v[152:155], v[2:3], off
	v_lshl_add_u64 v[2:3], v[2:3], 0, s[8:9]
	global_load_dwordx4 v[156:159], v[2:3], off
	v_lshl_add_u64 v[2:3], v[2:3], 0, s[8:9]
	s_waitcnt vmcnt(15)
	v_cvt_pk_bf16_f32 v60, v60, v61
	v_cvt_pk_bf16_f32 v61, v62, v63
	global_store_dwordx2 v[4:5], v[60:61], off
	v_lshl_add_u64 v[4:5], v[4:5], 0, s[0:1]
	s_waitcnt vmcnt(15)
	v_cvt_pk_bf16_f32 v64, v64, v65
	v_cvt_pk_bf16_f32 v65, v66, v67
	global_store_dwordx2 v[4:5], v[64:65], off
	v_lshl_add_u64 v[4:5], v[4:5], 0, s[0:1]
	s_waitcnt vmcnt(15)
	v_cvt_pk_bf16_f32 v68, v68, v69
	v_cvt_pk_bf16_f32 v69, v70, v71
	global_store_dwordx2 v[4:5], v[68:69], off
	v_lshl_add_u64 v[4:5], v[4:5], 0, s[0:1]
	s_waitcnt vmcnt(15)
	v_cvt_pk_bf16_f32 v72, v72, v73
	v_cvt_pk_bf16_f32 v73, v74, v75
	global_store_dwordx2 v[4:5], v[72:73], off
	v_lshl_add_u64 v[4:5], v[4:5], 0, s[0:1]
	s_waitcnt vmcnt(15)
	v_cvt_pk_bf16_f32 v112, v112, v113
	v_cvt_pk_bf16_f32 v113, v114, v115
	global_store_dwordx2 v[4:5], v[112:113], off
	v_lshl_add_u64 v[4:5], v[4:5], 0, s[0:1]
	s_waitcnt vmcnt(15)
	v_cvt_pk_bf16_f32 v116, v116, v117
	v_cvt_pk_bf16_f32 v117, v118, v119
	global_store_dwordx2 v[4:5], v[116:117], off
	v_lshl_add_u64 v[4:5], v[4:5], 0, s[0:1]
	s_waitcnt vmcnt(15)
	v_cvt_pk_bf16_f32 v120, v120, v121
	v_cvt_pk_bf16_f32 v121, v122, v123
	global_store_dwordx2 v[4:5], v[120:121], off
	v_lshl_add_u64 v[4:5], v[4:5], 0, s[0:1]
	s_waitcnt vmcnt(15)
	v_cvt_pk_bf16_f32 v124, v124, v125
	v_cvt_pk_bf16_f32 v125, v126, v127
	global_store_dwordx2 v[4:5], v[124:125], off
	v_lshl_add_u64 v[4:5], v[4:5], 0, s[0:1]
	global_load_dwordx4 v[60:63], v[2:3], off
	v_lshl_add_u64 v[2:3], v[2:3], 0, s[8:9]
	global_load_dwordx4 v[64:67], v[2:3], off
	v_lshl_add_u64 v[2:3], v[2:3], 0, s[8:9]
	global_load_dwordx4 v[68:71], v[2:3], off
	v_lshl_add_u64 v[2:3], v[2:3], 0, s[8:9]
	global_load_dwordx4 v[72:75], v[2:3], off
	v_lshl_add_u64 v[2:3], v[2:3], 0, s[8:9]
	global_load_dwordx4 v[112:115], v[2:3], off
	v_lshl_add_u64 v[2:3], v[2:3], 0, s[8:9]
	global_load_dwordx4 v[116:119], v[2:3], off
	v_lshl_add_u64 v[2:3], v[2:3], 0, s[8:9]
	global_load_dwordx4 v[120:123], v[2:3], off
	v_lshl_add_u64 v[2:3], v[2:3], 0, s[8:9]
	global_load_dwordx4 v[124:127], v[2:3], off
	v_lshl_add_u64 v[2:3], v[2:3], 0, s[8:9]
	s_waitcnt vmcnt(23)
	v_cvt_pk_bf16_f32 v128, v128, v129
	v_cvt_pk_bf16_f32 v129, v130, v131
	global_store_dwordx2 v[4:5], v[128:129], off
	v_lshl_add_u64 v[4:5], v[4:5], 0, s[0:1]
	s_waitcnt vmcnt(23)
	v_cvt_pk_bf16_f32 v132, v132, v133
	v_cvt_pk_bf16_f32 v133, v134, v135
	global_store_dwordx2 v[4:5], v[132:133], off
	v_lshl_add_u64 v[4:5], v[4:5], 0, s[0:1]
	s_waitcnt vmcnt(23)
	v_cvt_pk_bf16_f32 v136, v136, v137
	v_cvt_pk_bf16_f32 v137, v138, v139
	global_store_dwordx2 v[4:5], v[136:137], off
	v_lshl_add_u64 v[4:5], v[4:5], 0, s[0:1]
	s_waitcnt vmcnt(23)
	v_cvt_pk_bf16_f32 v140, v140, v141
	v_cvt_pk_bf16_f32 v141, v142, v143
	global_store_dwordx2 v[4:5], v[140:141], off
	v_lshl_add_u64 v[4:5], v[4:5], 0, s[0:1]
	s_waitcnt vmcnt(23)
; __device__ __forceinline__ void phase0(const Params& P, char* lds) {
;     ...
;   const size_t n4 = (size_t)TOK * DM / 4;
;   for (size_t i = (size_t)bid * NTH + tid; i < n4; i += (size_t)G * NTH) {
;     f32x4 v = ((const f32x4*)P.x)[i];
;     u32x2 w = {cvtpk(v[0], v[1]), cvtpk(v[2], v[3])};
;     ((u32x2*)P_xb)[i] = w;
;   }
	v_cvt_pk_bf16_f32 v144, v144, v145
	v_cvt_pk_bf16_f32 v145, v146, v147
	global_store_dwordx2 v[4:5], v[144:145], off
	v_lshl_add_u64 v[4:5], v[4:5], 0, s[0:1]
	s_waitcnt vmcnt(23)
	v_cvt_pk_bf16_f32 v148, v148, v149
	v_cvt_pk_bf16_f32 v149, v150, v151
	global_store_dwordx2 v[4:5], v[148:149], off
	v_lshl_add_u64 v[4:5], v[4:5], 0, s[0:1]
	s_waitcnt vmcnt(23)
	v_cvt_pk_bf16_f32 v152, v152, v153
	v_cvt_pk_bf16_f32 v153, v154, v155
	global_store_dwordx2 v[4:5], v[152:153], off
	v_lshl_add_u64 v[4:5], v[4:5], 0, s[0:1]
	s_waitcnt vmcnt(23)
	v_cvt_pk_bf16_f32 v156, v156, v157
	v_cvt_pk_bf16_f32 v157, v158, v159
	global_store_dwordx2 v[4:5], v[156:157], off
	v_lshl_add_u64 v[4:5], v[4:5], 0, s[0:1]
	global_load_dwordx4 v[128:131], v[2:3], off
	v_lshl_add_u64 v[2:3], v[2:3], 0, s[8:9]
	global_load_dwordx4 v[132:135], v[2:3], off
	v_lshl_add_u64 v[2:3], v[2:3], 0, s[8:9]
	global_load_dwordx4 v[136:139], v[2:3], off
	v_lshl_add_u64 v[2:3], v[2:3], 0, s[8:9]
	global_load_dwordx4 v[140:143], v[2:3], off
	v_lshl_add_u64 v[2:3], v[2:3], 0, s[8:9]
	global_load_dwordx4 v[144:147], v[2:3], off
	v_lshl_add_u64 v[2:3], v[2:3], 0, s[8:9]
	global_load_dwordx4 v[148:151], v[2:3], off
	v_lshl_add_u64 v[2:3], v[2:3], 0, s[8:9]
	global_load_dwordx4 v[152:155], v[2:3], off
	v_lshl_add_u64 v[2:3], v[2:3], 0, s[8:9]
	global_load_dwordx4 v[156:159], v[2:3], off
	v_lshl_add_u64 v[2:3], v[2:3], 0, s[8:9]
	s_waitcnt vmcnt(23)
	v_cvt_pk_bf16_f32 v60, v60, v61
	v_cvt_pk_bf16_f32 v61, v62, v63
	global_store_dwordx2 v[4:5], v[60:61], off
	v_lshl_add_u64 v[4:5], v[4:5], 0, s[0:1]
	s_waitcnt vmcnt(23)
	v_cvt_pk_bf16_f32 v64, v64, v65
	v_cvt_pk_bf16_f32 v65, v66, v67
	global_store_dwordx2 v[4:5], v[64:65], off
	v_lshl_add_u64 v[4:5], v[4:5], 0, s[0:1]
	s_waitcnt vmcnt(23)
	v_cvt_pk_bf16_f32 v68, v68, v69
	v_cvt_pk_bf16_f32 v69, v70, v71
	global_store_dwordx2 v[4:5], v[68:69], off
	v_lshl_add_u64 v[4:5], v[4:5], 0, s[0:1]
	s_waitcnt vmcnt(23)
	v_cvt_pk_bf16_f32 v72, v72, v73
	v_cvt_pk_bf16_f32 v73, v74, v75
	global_store_dwordx2 v[4:5], v[72:73], off
	v_lshl_add_u64 v[4:5], v[4:5], 0, s[0:1]
	s_waitcnt vmcnt(23)
	v_cvt_pk_bf16_f32 v112, v112, v113
	v_cvt_pk_bf16_f32 v113, v114, v115
	global_store_dwordx2 v[4:5], v[112:113], off
	v_lshl_add_u64 v[4:5], v[4:5], 0, s[0:1]
	s_waitcnt vmcnt(23)
	v_cvt_pk_bf16_f32 v116, v116, v117
	v_cvt_pk_bf16_f32 v117, v118, v119
	global_store_dwordx2 v[4:5], v[116:117], off
	v_lshl_add_u64 v[4:5], v[4:5], 0, s[0:1]
	s_waitcnt vmcnt(23)
	v_cvt_pk_bf16_f32 v120, v120, v121
	v_cvt_pk_bf16_f32 v121, v122, v123
	global_store_dwordx2 v[4:5], v[120:121], off
	v_lshl_add_u64 v[4:5], v[4:5], 0, s[0:1]
	s_waitcnt vmcnt(23)
	v_cvt_pk_bf16_f32 v124, v124, v125
	v_cvt_pk_bf16_f32 v125, v126, v127
	global_store_dwordx2 v[4:5], v[124:125], off
	v_lshl_add_u64 v[4:5], v[4:5], 0, s[0:1]
	global_load_dwordx4 v[60:63], v[2:3], off
	v_lshl_add_u64 v[2:3], v[2:3], 0, s[8:9]
	global_load_dwordx4 v[64:67], v[2:3], off
	v_lshl_add_u64 v[2:3], v[2:3], 0, s[8:9]
	global_load_dwordx4 v[68:71], v[2:3], off
	v_lshl_add_u64 v[2:3], v[2:3], 0, s[8:9]
	global_load_dwordx4 v[72:75], v[2:3], off
	v_lshl_add_u64 v[2:3], v[2:3], 0, s[8:9]
	global_load_dwordx4 v[112:115], v[2:3], off
	v_lshl_add_u64 v[2:3], v[2:3], 0, s[8:9]
	global_load_dwordx4 v[116:119], v[2:3], off
	v_lshl_add_u64 v[2:3], v[2:3], 0, s[8:9]
	global_load_dwordx4 v[120:123], v[2:3], off
	v_lshl_add_u64 v[2:3], v[2:3], 0, s[8:9]
	global_load_dwordx4 v[124:127], v[2:3], off
	v_lshl_add_u64 v[2:3], v[2:3], 0, s[8:9]
	s_waitcnt vmcnt(23)
	v_cvt_pk_bf16_f32 v128, v128, v129
	v_cvt_pk_bf16_f32 v129, v130, v131
	global_store_dwordx2 v[4:5], v[128:129], off
	v_lshl_add_u64 v[4:5], v[4:5], 0, s[0:1]
	s_waitcnt vmcnt(23)
	v_cvt_pk_bf16_f32 v132, v132, v133
	v_cvt_pk_bf16_f32 v133, v134, v135
	global_store_dwordx2 v[4:5], v[132:133], off
	v_lshl_add_u64 v[4:5], v[4:5], 0, s[0:1]
	s_waitcnt vmcnt(23)
	v_cvt_pk_bf16_f32 v136, v136, v137
	v_cvt_pk_bf16_f32 v137, v138, v139
	global_store_dwordx2 v[4:5], v[136:137], off
	v_lshl_add_u64 v[4:5], v[4:5], 0, s[0:1]
	s_waitcnt vmcnt(23)
	v_cvt_pk_bf16_f32 v140, v140, v141
	v_cvt_pk_bf16_f32 v141, v142, v143
	global_store_dwordx2 v[4:5], v[140:141], off
	v_lshl_add_u64 v[4:5], v[4:5], 0, s[0:1]
	s_waitcnt vmcnt(23)
	v_cvt_pk_bf16_f32 v144, v144, v145
	v_cvt_pk_bf16_f32 v145, v146, v147
	global_store_dwordx2 v[4:5], v[144:145], off
	v_lshl_add_u64 v[4:5], v[4:5], 0, s[0:1]
	s_waitcnt vmcnt(23)
	v_cvt_pk_bf16_f32 v148, v148, v149
	v_cvt_pk_bf16_f32 v149, v150, v151
	global_store_dwordx2 v[4:5], v[148:149], off
	v_lshl_add_u64 v[4:5], v[4:5], 0, s[0:1]
	s_waitcnt vmcnt(23)
	v_cvt_pk_bf16_f32 v152, v152, v153
	v_cvt_pk_bf16_f32 v153, v154, v155
	global_store_dwordx2 v[4:5], v[152:153], off
	v_lshl_add_u64 v[4:5], v[4:5], 0, s[0:1]
	s_waitcnt vmcnt(23)
	v_cvt_pk_bf16_f32 v156, v156, v157
	v_cvt_pk_bf16_f32 v157, v158, v159
	global_store_dwordx2 v[4:5], v[156:157], off
	v_lshl_add_u64 v[4:5], v[4:5], 0, s[0:1]
	global_load_dwordx4 v[128:131], v[2:3], off
	v_lshl_add_u64 v[2:3], v[2:3], 0, s[8:9]
	global_load_dwordx4 v[132:135], v[2:3], off
	v_lshl_add_u64 v[2:3], v[2:3], 0, s[8:9]
	global_load_dwordx4 v[136:139], v[2:3], off
	v_lshl_add_u64 v[2:3], v[2:3], 0, s[8:9]
	global_load_dwordx4 v[140:143], v[2:3], off
	v_lshl_add_u64 v[2:3], v[2:3], 0, s[8:9]
	global_load_dwordx4 v[144:147], v[2:3], off
	v_lshl_add_u64 v[2:3], v[2:3], 0, s[8:9]
	global_load_dwordx4 v[148:151], v[2:3], off
	v_lshl_add_u64 v[2:3], v[2:3], 0, s[8:9]
	global_load_dwordx4 v[152:155], v[2:3], off
	v_lshl_add_u64 v[2:3], v[2:3], 0, s[8:9]
	global_load_dwordx4 v[156:159], v[2:3], off
	v_lshl_add_u64 v[2:3], v[2:3], 0, s[8:9]
	s_waitcnt vmcnt(23)
; __device__ __forceinline__ void phase0(const Params& P, char* lds) {
;     ...
;   const size_t n4 = (size_t)TOK * DM / 4;
;   for (size_t i = (size_t)bid * NTH + tid; i < n4; i += (size_t)G * NTH) {
;     f32x4 v = ((const f32x4*)P.x)[i];
;     u32x2 w = {cvtpk(v[0], v[1]), cvtpk(v[2], v[3])};
;     ((u32x2*)P_xb)[i] = w;
;   }
	v_cvt_pk_bf16_f32 v60, v60, v61
	v_cvt_pk_bf16_f32 v61, v62, v63
	global_store_dwordx2 v[4:5], v[60:61], off
	v_lshl_add_u64 v[4:5], v[4:5], 0, s[0:1]
	s_waitcnt vmcnt(23)
	v_cvt_pk_bf16_f32 v64, v64, v65
	v_cvt_pk_bf16_f32 v65, v66, v67
	global_store_dwordx2 v[4:5], v[64:65], off
	v_lshl_add_u64 v[4:5], v[4:5], 0, s[0:1]
	s_waitcnt vmcnt(23)
	v_cvt_pk_bf16_f32 v68, v68, v69
	v_cvt_pk_bf16_f32 v69, v70, v71
	global_store_dwordx2 v[4:5], v[68:69], off
	v_lshl_add_u64 v[4:5], v[4:5], 0, s[0:1]
	s_waitcnt vmcnt(23)
	v_cvt_pk_bf16_f32 v72, v72, v73
	v_cvt_pk_bf16_f32 v73, v74, v75
	global_store_dwordx2 v[4:5], v[72:73], off
	v_lshl_add_u64 v[4:5], v[4:5], 0, s[0:1]
	s_waitcnt vmcnt(23)
	v_cvt_pk_bf16_f32 v112, v112, v113
	v_cvt_pk_bf16_f32 v113, v114, v115
	global_store_dwordx2 v[4:5], v[112:113], off
	v_lshl_add_u64 v[4:5], v[4:5], 0, s[0:1]
	s_waitcnt vmcnt(23)
	v_cvt_pk_bf16_f32 v116, v116, v117
	v_cvt_pk_bf16_f32 v117, v118, v119
	global_store_dwordx2 v[4:5], v[116:117], off
	v_lshl_add_u64 v[4:5], v[4:5], 0, s[0:1]
	s_waitcnt vmcnt(23)
	v_cvt_pk_bf16_f32 v120, v120, v121
	v_cvt_pk_bf16_f32 v121, v122, v123
	global_store_dwordx2 v[4:5], v[120:121], off
	v_lshl_add_u64 v[4:5], v[4:5], 0, s[0:1]
	s_waitcnt vmcnt(23)
	v_cvt_pk_bf16_f32 v124, v124, v125
	v_cvt_pk_bf16_f32 v125, v126, v127
	global_store_dwordx2 v[4:5], v[124:125], off
	v_lshl_add_u64 v[4:5], v[4:5], 0, s[0:1]
	global_load_dwordx4 v[60:63], v[2:3], off
	v_lshl_add_u64 v[2:3], v[2:3], 0, s[8:9]
	global_load_dwordx4 v[64:67], v[2:3], off
	v_lshl_add_u64 v[2:3], v[2:3], 0, s[8:9]
	global_load_dwordx4 v[68:71], v[2:3], off
	v_lshl_add_u64 v[2:3], v[2:3], 0, s[8:9]
	global_load_dwordx4 v[72:75], v[2:3], off
	v_lshl_add_u64 v[2:3], v[2:3], 0, s[8:9]
	global_load_dwordx4 v[112:115], v[2:3], off
	v_lshl_add_u64 v[2:3], v[2:3], 0, s[8:9]
	global_load_dwordx4 v[116:119], v[2:3], off
	v_lshl_add_u64 v[2:3], v[2:3], 0, s[8:9]
	global_load_dwordx4 v[120:123], v[2:3], off
	v_lshl_add_u64 v[2:3], v[2:3], 0, s[8:9]
	global_load_dwordx4 v[124:127], v[2:3], off
	v_lshl_add_u64 v[2:3], v[2:3], 0, s[8:9]
	s_waitcnt vmcnt(23)
	v_cvt_pk_bf16_f32 v128, v128, v129
	v_cvt_pk_bf16_f32 v129, v130, v131
	global_store_dwordx2 v[4:5], v[128:129], off
	v_lshl_add_u64 v[4:5], v[4:5], 0, s[0:1]
	s_waitcnt vmcnt(23)
	v_cvt_pk_bf16_f32 v132, v132, v133
	v_cvt_pk_bf16_f32 v133, v134, v135
	global_store_dwordx2 v[4:5], v[132:133], off
	v_lshl_add_u64 v[4:5], v[4:5], 0, s[0:1]
	s_waitcnt vmcnt(23)
	v_cvt_pk_bf16_f32 v136, v136, v137
	v_cvt_pk_bf16_f32 v137, v138, v139
	global_store_dwordx2 v[4:5], v[136:137], off
	v_lshl_add_u64 v[4:5], v[4:5], 0, s[0:1]
	s_waitcnt vmcnt(23)
	v_cvt_pk_bf16_f32 v140, v140, v141
	v_cvt_pk_bf16_f32 v141, v142, v143
	global_store_dwordx2 v[4:5], v[140:141], off
	v_lshl_add_u64 v[4:5], v[4:5], 0, s[0:1]
	s_waitcnt vmcnt(23)
	v_cvt_pk_bf16_f32 v144, v144, v145
	v_cvt_pk_bf16_f32 v145, v146, v147
	global_store_dwordx2 v[4:5], v[144:145], off
	v_lshl_add_u64 v[4:5], v[4:5], 0, s[0:1]
	s_waitcnt vmcnt(23)
	v_cvt_pk_bf16_f32 v148, v148, v149
	v_cvt_pk_bf16_f32 v149, v150, v151
	global_store_dwordx2 v[4:5], v[148:149], off
	v_lshl_add_u64 v[4:5], v[4:5], 0, s[0:1]
	s_waitcnt vmcnt(23)
	v_cvt_pk_bf16_f32 v152, v152, v153
	v_cvt_pk_bf16_f32 v153, v154, v155
	global_store_dwordx2 v[4:5], v[152:153], off
	v_lshl_add_u64 v[4:5], v[4:5], 0, s[0:1]
	s_waitcnt vmcnt(23)
; __device__ __forceinline__ void phase0(const Params& P, char* lds) {
;     ...
;   const size_t n4 = (size_t)TOK * DM / 4;
;   for (size_t i = (size_t)bid * NTH + tid; i < n4; i += (size_t)G * NTH) {
;     f32x4 v = ((const f32x4*)P.x)[i];
;     u32x2 w = {cvtpk(v[0], v[1]), cvtpk(v[2], v[3])};
;     ((u32x2*)P_xb)[i] = w;
;   }
	v_cvt_pk_bf16_f32 v156, v156, v157
	v_cvt_pk_bf16_f32 v157, v158, v159
	global_store_dwordx2 v[4:5], v[156:157], off
	v_lshl_add_u64 v[4:5], v[4:5], 0, s[0:1]
	global_load_dwordx4 v[128:131], v[2:3], off
	v_lshl_add_u64 v[2:3], v[2:3], 0, s[8:9]
	global_load_dwordx4 v[132:135], v[2:3], off
	v_lshl_add_u64 v[2:3], v[2:3], 0, s[8:9]
	global_load_dwordx4 v[136:139], v[2:3], off
	v_lshl_add_u64 v[2:3], v[2:3], 0, s[8:9]
	global_load_dwordx4 v[140:143], v[2:3], off
	v_lshl_add_u64 v[2:3], v[2:3], 0, s[8:9]
	global_load_dwordx4 v[144:147], v[2:3], off
	v_lshl_add_u64 v[2:3], v[2:3], 0, s[8:9]
	global_load_dwordx4 v[148:151], v[2:3], off
	v_lshl_add_u64 v[2:3], v[2:3], 0, s[8:9]
	global_load_dwordx4 v[152:155], v[2:3], off
	v_lshl_add_u64 v[2:3], v[2:3], 0, s[8:9]
	global_load_dwordx4 v[156:159], v[2:3], off
	v_lshl_add_u64 v[2:3], v[2:3], 0, s[8:9]
	s_waitcnt vmcnt(23)
	v_cvt_pk_bf16_f32 v60, v60, v61
	v_cvt_pk_bf16_f32 v61, v62, v63
	global_store_dwordx2 v[4:5], v[60:61], off
	v_lshl_add_u64 v[4:5], v[4:5], 0, s[0:1]
	s_waitcnt vmcnt(23)
	v_cvt_pk_bf16_f32 v64, v64, v65
	v_cvt_pk_bf16_f32 v65, v66, v67
	global_store_dwordx2 v[4:5], v[64:65], off
	v_lshl_add_u64 v[4:5], v[4:5], 0, s[0:1]
	s_waitcnt vmcnt(23)
	v_cvt_pk_bf16_f32 v68, v68, v69
	v_cvt_pk_bf16_f32 v69, v70, v71
	global_store_dwordx2 v[4:5], v[68:69], off
	v_lshl_add_u64 v[4:5], v[4:5], 0, s[0:1]
	s_waitcnt vmcnt(23)
	v_cvt_pk_bf16_f32 v72, v72, v73
	v_cvt_pk_bf16_f32 v73, v74, v75
	global_store_dwordx2 v[4:5], v[72:73], off
	v_lshl_add_u64 v[4:5], v[4:5], 0, s[0:1]
	s_waitcnt vmcnt(23)
	v_cvt_pk_bf16_f32 v112, v112, v113
	v_cvt_pk_bf16_f32 v113, v114, v115
	global_store_dwordx2 v[4:5], v[112:113], off
	v_lshl_add_u64 v[4:5], v[4:5], 0, s[0:1]
	s_waitcnt vmcnt(23)
	v_cvt_pk_bf16_f32 v116, v116, v117
	v_cvt_pk_bf16_f32 v117, v118, v119
	global_store_dwordx2 v[4:5], v[116:117], off
	v_lshl_add_u64 v[4:5], v[4:5], 0, s[0:1]
	s_waitcnt vmcnt(23)
	v_cvt_pk_bf16_f32 v120, v120, v121
	v_cvt_pk_bf16_f32 v121, v122, v123
	global_store_dwordx2 v[4:5], v[120:121], off
	v_lshl_add_u64 v[4:5], v[4:5], 0, s[0:1]
	s_waitcnt vmcnt(23)
	v_cvt_pk_bf16_f32 v124, v124, v125
	v_cvt_pk_bf16_f32 v125, v126, v127
	global_store_dwordx2 v[4:5], v[124:125], off
	v_lshl_add_u64 v[4:5], v[4:5], 0, s[0:1]
	s_waitcnt vmcnt(15)
	v_cvt_pk_bf16_f32 v128, v128, v129
	v_cvt_pk_bf16_f32 v129, v130, v131
	global_store_dwordx2 v[4:5], v[128:129], off
	v_lshl_add_u64 v[4:5], v[4:5], 0, s[0:1]
	s_waitcnt vmcnt(15)
	v_cvt_pk_bf16_f32 v132, v132, v133
	v_cvt_pk_bf16_f32 v133, v134, v135
	global_store_dwordx2 v[4:5], v[132:133], off
	v_lshl_add_u64 v[4:5], v[4:5], 0, s[0:1]
	s_waitcnt vmcnt(15)
	v_cvt_pk_bf16_f32 v136, v136, v137
	v_cvt_pk_bf16_f32 v137, v138, v139
	global_store_dwordx2 v[4:5], v[136:137], off
	v_lshl_add_u64 v[4:5], v[4:5], 0, s[0:1]
	s_waitcnt vmcnt(15)
	v_cvt_pk_bf16_f32 v140, v140, v141
	v_cvt_pk_bf16_f32 v141, v142, v143
	global_store_dwordx2 v[4:5], v[140:141], off
	v_lshl_add_u64 v[4:5], v[4:5], 0, s[0:1]
	s_waitcnt vmcnt(15)
	v_cvt_pk_bf16_f32 v144, v144, v145
	v_cvt_pk_bf16_f32 v145, v146, v147
	global_store_dwordx2 v[4:5], v[144:145], off
	v_lshl_add_u64 v[4:5], v[4:5], 0, s[0:1]
	s_waitcnt vmcnt(15)
	v_cvt_pk_bf16_f32 v148, v148, v149
	v_cvt_pk_bf16_f32 v149, v150, v151
	global_store_dwordx2 v[4:5], v[148:149], off
	v_lshl_add_u64 v[4:5], v[4:5], 0, s[0:1]
	s_waitcnt vmcnt(15)
	v_cvt_pk_bf16_f32 v152, v152, v153
	v_cvt_pk_bf16_f32 v153, v154, v155
	global_store_dwordx2 v[4:5], v[152:153], off
	v_lshl_add_u64 v[4:5], v[4:5], 0, s[0:1]
	s_waitcnt vmcnt(15)
	v_cvt_pk_bf16_f32 v156, v156, v157
	v_cvt_pk_bf16_f32 v157, v158, v159
	global_store_dwordx2 v[4:5], v[156:157], off
	v_lshl_add_u64 v[4:5], v[4:5], 0, s[0:1]
	s_branch .LBB0_76
